# 13 XCD-local seams (added retention scan seams by permuting the scan's block->work map so ret1/scan/ret2 of a head pair stay on one XCD)
# speedup vs baseline: 1.0351x; 1.0075x over previous
.Lxloc_5:
	v_mov_b32_e32 v0, 0x2000
	v_mov_b32_e32 v1, 1
	s_waitcnt vmcnt(0)
	buffer_inv sc1
	global_atomic_add v0, v1, s[6:7] offset:1024
	s_waitcnt vmcnt(0)

.LBB0_755:
	s_waitcnt vmcnt(0)
	s_and_b32 s3, s2, 7
	s_lshr_b32 s16, s2, 3
	s_lshl_b32 s3, s3, 4
	s_add_i32 s3, s3, s16
	s_cmp_lt_u32 s16, 16
	s_cselect_b32 s3, s3, 0xff
	s_cmp_eq_u32 s94, 0x100
	s_cselect_b32 s16, s3, s2
	v_lshl_add_u32 v2, s16, 9, v254
	s_mov_b32 s3, 0x10000
	v_cmp_gt_i32_e32 vcc, s3, v2
	s_and_saveexec_b64 s[4:5], vcc
	s_cbranch_execz .LBB0_764
	s_add_u32 s6, s90, 0x5b00000
	s_addc_u32 s7, s91, 0
	s_add_u32 s8, s90, 0x1d500000
	s_addc_u32 s9, s91, 0
	s_lshl_b32 s16, s94, 9
	s_mov_b64 s[10:11], 0
	s_waitcnt lgkmcnt(0)
	v_mov_b32_e32 v1, 0
	s_movk_i32 s17, 0x4000
	s_mov_b32 s18, 0x8000
	s_mov_b32 s19, 0xc000
	s_mov_b32 s20, 0x14000
	s_mov_b32 s21, 0x18000
	s_mov_b32 s22, 0x1c000
	s_mov_b32 s23, 0x20000
	s_mov_b32 s24, 0x24000
	s_mov_b32 s25, 0x28000
	s_mov_b32 s26, 0x2c000
	s_mov_b32 s27, 0x30000
	s_mov_b32 s28, 0x34000
	s_mov_b32 s29, 0x38000
	s_mov_b32 s30, 0x3c000
	s_mov_b32 s31, 0x40000
	s_mov_b32 s33, 0x44000
	s_mov_b32 s34, 0x48000
	s_mov_b32 s35, 0x4c000
	s_mov_b32 s36, 0x50000
	s_mov_b32 s37, 0x54000
	s_mov_b32 s38, 0x58000
	s_mov_b32 s39, 0x5c000
	s_mov_b32 s40, 0x60000
	s_mov_b32 s41, 0x64000
	s_mov_b32 s42, 0x68000
	s_mov_b32 s43, 0x6c000
	s_mov_b32 s44, 0x70000
	s_mov_b32 s45, 0x74000
	s_mov_b32 s46, 0xffff
	v_mov_b32_e32 v3, 0xbfb906ce
	v_mov_b32_e32 v4, 0xc03963dd
	s_branch .LBB0_759

.LBB0_797:
	s_andn2_saveexec_b64 s[6:7], s[6:7]
	s_cbranch_execz .LBB0_815
	s_cmp_eq_u32 s98, 1
	s_cbranch_scc1 .Lxloc_6
	s_mov_b64 s[6:7], exec
	buffer_wbl2 sc1
	s_waitcnt lgkmcnt(0)
	s_waitcnt vmcnt(0)
	v_mbcnt_lo_u32_b32 v1, s6, 0
	v_mbcnt_hi_u32_b32 v1, s7, v1
	v_cmp_eq_u32_e32 vcc, 0, v1
	s_and_saveexec_b64 s[8:9], vcc
	s_cbranch_execz .LBB0_800
	s_bcnt1_i32_b64 s3, s[6:7]
	v_mov_b32_e32 v2, 0x7000
	v_mov_b32_e32 v3, s3
	global_atomic_add v2, v2, v3, s[90:91] offset:1024 sc0
.LBB0_800:
	s_or_b64 exec, exec, s[8:9]
	v_cvt_f32_u32_e32 v3, v0
	s_waitcnt vmcnt(0)
	v_readfirstlane_b32 s3, v2
	s_add_u32 s8, s90, 0x7500
	s_addc_u32 s9, s91, 0
	v_rcp_iflag_f32_e32 v3, v3
	v_add_u32_e32 v1, s3, v1
	v_add_u32_e32 v4, 1, v1
	s_mov_b64 s[10:11], -1
	v_mul_f32_e32 v2, 0x4f7ffffe, v3
	v_cvt_u32_f32_e32 v2, v2
	v_sub_u32_e32 v3, 0, v0
	v_mul_lo_u32 v3, v3, v2
	v_mul_hi_u32 v3, v2, v3
	v_add_u32_e32 v2, v2, v3
	v_mul_hi_u32 v2, v1, v2
	v_mul_lo_u32 v3, v2, v0
	v_sub_u32_e32 v1, v1, v3
	v_add_u32_e32 v5, 1, v2
	v_cmp_ge_u32_e32 vcc, v1, v0
	v_sub_u32_e32 v3, v1, v0
	s_nop 0
	v_cndmask_b32_e32 v2, v2, v5, vcc
	v_cndmask_b32_e32 v1, v1, v3, vcc
	v_add_u32_e32 v3, 1, v2
	v_cmp_ge_u32_e32 vcc, v1, v0
	s_nop 1
	v_cndmask_b32_e32 v2, v2, v3, vcc
	v_mul_lo_u32 v1, v0, v2
	v_add_u32_e32 v0, v1, v0
	v_cmp_ne_u32_e32 vcc, v4, v0
	v_mov_b64_e32 v[0:1], s[8:9]
	s_and_saveexec_b64 s[6:7], vcc
	s_cbranch_execz .LBB0_812
	v_mov_b32_e32 v0, 0
	global_load_dword v1, v0, s[8:9] sc1
	s_mov_b64 s[14:15], 0
	s_waitcnt vmcnt(0)
	v_cmp_eq_u32_e32 vcc, v1, v2
	s_and_saveexec_b64 s[12:13], vcc
	s_cbranch_execz .LBB0_811
	s_add_u32 s10, s90, 0x4200
	s_addc_u32 s11, s91, 0
	s_mov_b32 s3, 1
	s_branch .LBB0_804

.LBB0_1680:
	s_andn2_saveexec_b64 s[6:7], s[6:7]
	s_cbranch_execz .LBB0_1698
	s_cmp_eq_u32 s98, 1
	s_cbranch_scc1 .Lxloc_15
	s_mov_b64 s[6:7], exec
	buffer_wbl2 sc1
	s_waitcnt lgkmcnt(0)
	s_waitcnt vmcnt(0)
	v_mbcnt_lo_u32_b32 v1, s6, 0
	v_mbcnt_hi_u32_b32 v1, s7, v1
	v_cmp_eq_u32_e32 vcc, 0, v1
	s_and_saveexec_b64 s[8:9], vcc
	s_cbranch_execz .LBB0_1683
	s_bcnt1_i32_b64 s3, s[6:7]
	v_mov_b32_e32 v2, 0x7000
	v_mov_b32_e32 v3, s3
	global_atomic_add v2, v2, v3, s[90:91] offset:1024 sc0
.LBB0_1683:
	s_or_b64 exec, exec, s[8:9]
	v_cvt_f32_u32_e32 v3, v0
	s_waitcnt vmcnt(0)
	v_readfirstlane_b32 s3, v2
	s_add_u32 s8, s90, 0x7500
	s_addc_u32 s9, s91, 0
	v_rcp_iflag_f32_e32 v3, v3
	v_add_u32_e32 v1, s3, v1
	v_add_u32_e32 v4, 1, v1
	s_mov_b64 s[10:11], -1
	v_mul_f32_e32 v2, 0x4f7ffffe, v3
	v_cvt_u32_f32_e32 v2, v2
	v_sub_u32_e32 v3, 0, v0
	v_mul_lo_u32 v3, v3, v2
	v_mul_hi_u32 v3, v2, v3
	v_add_u32_e32 v2, v2, v3
	v_mul_hi_u32 v2, v1, v2
	v_mul_lo_u32 v3, v2, v0
	v_sub_u32_e32 v1, v1, v3
	v_add_u32_e32 v5, 1, v2
	v_cmp_ge_u32_e32 vcc, v1, v0
	v_sub_u32_e32 v3, v1, v0
	s_nop 0
	v_cndmask_b32_e32 v2, v2, v5, vcc
	v_cndmask_b32_e32 v1, v1, v3, vcc
	v_add_u32_e32 v3, 1, v2
	v_cmp_ge_u32_e32 vcc, v1, v0
	s_nop 1
	v_cndmask_b32_e32 v2, v2, v3, vcc
	v_mul_lo_u32 v1, v0, v2
	v_add_u32_e32 v0, v1, v0
	v_cmp_ne_u32_e32 vcc, v4, v0
	v_mov_b64_e32 v[0:1], s[8:9]
	s_and_saveexec_b64 s[6:7], vcc
	s_cbranch_execz .LBB0_1695
	v_mov_b32_e32 v0, 0
	global_load_dword v1, v0, s[8:9] sc1
	s_mov_b64 s[14:15], 0
	s_waitcnt vmcnt(0)
	v_cmp_eq_u32_e32 vcc, v1, v2
	s_and_saveexec_b64 s[12:13], vcc
	s_cbranch_execz .LBB0_1694
	s_add_u32 s10, s90, 0x4200
	s_addc_u32 s11, s91, 0
	s_mov_b32 s3, 1
	s_branch .LBB0_1687
